# decode combine: lam (exp(lq1.lk1)-exp(lq2.lk2)) computed once per wave and kept in a spare SGPR instead of per item
# speedup vs baseline: 1.0386x; 1.0002x over previous
_Z9hymba_fwd4Args:
	s_mov_b32 s99, 0
	s_load_dwordx2 s[92:93], s[0:1], 0xb0
	s_load_dwordx4 s[84:87], s[0:1], 0xa0
	s_load_dword s3, s[0:1], 0xb8
	s_load_dwordx8 s[4:11], s[0:1], 0x80
	s_waitcnt lgkmcnt(0)
	v_writelane_b32 v247, s4, 0
	s_nop 1
	v_writelane_b32 v247, s5, 1
	v_writelane_b32 v247, s6, 2
	v_writelane_b32 v247, s7, 3
	v_writelane_b32 v247, s8, 4
	v_writelane_b32 v247, s9, 5
	v_writelane_b32 v247, s10, 6
	v_writelane_b32 v247, s11, 7
	s_add_u32 s4, s0, 0xb8
	s_addc_u32 s5, s1, 0
	v_writelane_b32 v247, s4, 8
	v_readfirstlane_b32 s6, v0
	s_nop 0
	v_writelane_b32 v247, s5, 9
	v_writelane_b32 v247, s3, 10
	s_and_b32 s3, s3, 7
	s_cmp_lg_u32 s3, 0
	v_writelane_b32 v247, s2, 11
	v_writelane_b32 v247, s2, 12
	s_cbranch_scc1 .LBB0_2
	s_load_dword s2, s[0:1], 0xb8
	v_readlane_b32 s5, v247, 11
	s_ashr_i32 s3, s5, 31
	s_lshr_b32 s3, s3, 29
	s_add_i32 s3, s5, s3
	s_and_b32 s4, s3, -8
	s_waitcnt lgkmcnt(0)
	s_ashr_i32 s2, s2, 3
	s_sub_i32 s4, s5, s4
	s_mul_i32 s2, s2, s4
	s_ashr_i32 s3, s3, 3
	s_add_i32 s2, s2, s3
	v_writelane_b32 v247, s2, 12

.LBB0_384:
	s_or_b64 exec, exec, s[2:3]
	v_mov_b32_e32 v4, v168
	v_mov_b32_e32 v5, v172
	v_mov_b32_e32 v6, v176
	v_mov_b32_e32 v7, v164
	ds_write_b128 v230, v[4:7]
	v_mov_b32_e32 v4, v169
	v_mov_b32_e32 v5, v173
	v_mov_b32_e32 v6, v177
	v_mov_b32_e32 v7, v165
	ds_write_b128 v230, v[4:7] offset:16
	v_mov_b32_e32 v4, v170
	v_mov_b32_e32 v5, v174
	v_mov_b32_e32 v6, v178
	v_mov_b32_e32 v7, v166
	ds_write_b128 v230, v[4:7] offset:32
	v_mov_b32_e32 v4, v148
	v_mov_b32_e32 v5, v152
	v_mov_b32_e32 v6, v156
	v_mov_b32_e32 v7, v160
	s_add_i32 s2, 0, 0x10000
	ds_write_b128 v230, v[4:7] offset:256
	v_mov_b32_e32 v4, v149
	v_mov_b32_e32 v5, v153
	v_mov_b32_e32 v6, v157
	v_mov_b32_e32 v7, v161
	s_add_i32 s3, s2, s66
	v_mov_b32_e32 v164, v171
	v_mov_b32_e32 v165, v175
	v_mov_b32_e32 v166, v179
	ds_write_b128 v230, v[4:7] offset:272
	v_mov_b32_e32 v4, v150
	v_mov_b32_e32 v5, v154
	v_mov_b32_e32 v6, v158
	v_mov_b32_e32 v7, v162
	v_mov_b32_e32 v160, v151
	v_mov_b32_e32 v161, v155
	v_mov_b32_e32 v162, v159
	v_mov_b32_e32 v0, s3
	ds_write_b128 v230, v[164:167] offset:48
	ds_write_b128 v230, v[4:7] offset:288
	ds_write_b128 v230, v[160:163] offset:304
	s_waitcnt lgkmcnt(0)
	s_barrier
	ds_read2_b64 v[4:7], v0 offset1:16
	ds_read2_b64 v[8:11], v0 offset0:32 offset1:48
	ds_read2_b64 v[12:15], v0 offset0:64 offset1:80
	ds_read2_b64 v[16:19], v0 offset0:96 offset1:112
	s_add_i32 s2, s2, s1
	s_waitcnt lgkmcnt(3)
	v_max3_f32 v1, v4, s81, v6
	s_waitcnt lgkmcnt(2)
	v_max3_f32 v1, v1, v8, v10
	s_waitcnt lgkmcnt(1)
	v_max3_f32 v1, v1, v12, v14
	s_waitcnt lgkmcnt(0)
	v_max3_f32 v3, v1, v16, v18
	v_sub_f32_e32 v0, v4, v3
	v_exp_f32_e32 v0, v0
	v_add_u32_e32 v1, s67, v231
	v_fma_f32 v28, v0, v5, 0
	ds_read_b64 v[4:5], v1
	v_sub_f32_e32 v1, v6, v3
	v_exp_f32_e32 v6, v1
	v_add_u32_e32 v1, s28, v231
	ds_read_b64 v[20:21], v1
	v_sub_f32_e32 v1, v8, v3
	v_exp_f32_e32 v8, v1
	v_add_u32_e32 v1, s29, v231
	ds_read_b64 v[22:23], v1
	v_sub_f32_e32 v1, v10, v3
	v_exp_f32_e32 v10, v1
	v_add_u32_e32 v1, s24, v231
	ds_read_b64 v[24:25], v1
	v_sub_f32_e32 v1, v12, v3
	v_exp_f32_e32 v12, v1
	v_add_u32_e32 v1, s84, v231
	ds_read_b64 v[26:27], v1
	s_waitcnt lgkmcnt(4)
	v_pk_fma_f32 v[0:1], v[0:1], v[4:5], 0 op_sel_hi:[0,1,0]
	v_fmac_f32_e32 v28, v6, v7
	s_waitcnt lgkmcnt(3)
	v_pk_fma_f32 v[0:1], v[6:7], v[20:21], v[0:1] op_sel_hi:[0,1,1]
	v_sub_f32_e32 v4, v14, v3
	v_add_u32_e32 v5, s85, v231
	v_fmac_f32_e32 v28, v8, v9
	s_waitcnt lgkmcnt(2)
	v_pk_fma_f32 v[0:1], v[8:9], v[22:23], v[0:1] op_sel_hi:[0,1,1]
	v_exp_f32_e32 v4, v4
	ds_read_b64 v[6:7], v5
	v_sub_f32_e32 v5, v16, v3
	v_fmac_f32_e32 v28, v10, v11
	s_waitcnt lgkmcnt(2)
	v_pk_fma_f32 v[0:1], v[10:11], v[24:25], v[0:1] op_sel_hi:[0,1,1]
	v_exp_f32_e32 v8, v5
	v_sub_f32_e32 v3, v18, v3
	v_fmac_f32_e32 v28, v12, v13
	s_waitcnt lgkmcnt(1)
	v_pk_fma_f32 v[0:1], v[12:13], v[26:27], v[0:1] op_sel_hi:[0,1,1]
	v_exp_f32_e32 v12, v3
	v_fmac_f32_e32 v28, v4, v15
	v_fmac_f32_e32 v28, v8, v17
	v_add_u32_e32 v5, s26, v231
	v_fmac_f32_e32 v28, v12, v19
	v_add_u32_e32 v3, s94, v231
	ds_read_b64 v[10:11], v5
	ds_read_b64 v[14:15], v3
	v_div_scale_f32 v3, s[16:17], v28, v28, 1.0
	v_rcp_f32_e32 v5, v3
	s_mov_b32 s16, 0x42b17218
	v_fma_f32 v9, -v3, v5, 1.0
	v_fmac_f32_e32 v5, v9, v5
	v_div_scale_f32 v9, vcc, 1.0, v28, 1.0
	v_mul_f32_e32 v13, v9, v5
	v_fma_f32 v16, -v3, v13, v9
	v_fmac_f32_e32 v13, v16, v5
	v_fma_f32 v3, -v3, v13, v9
	v_div_fmas_f32 v3, v3, v5, v13
	v_div_fixup_f32 v16, v3, v28, 1.0
	v_mov_b32_e32 v3, s2
	ds_read2_b64 v[18:21], v3 offset1:16
	ds_read2_b64 v[22:25], v3 offset0:32 offset1:48
	ds_read2_b64 v[26:29], v3 offset0:64 offset1:80
	ds_read2_b64 v[30:33], v3 offset0:96 offset1:112
	v_add_u32_e32 v9, s95, v231
	s_waitcnt lgkmcnt(3)
	v_max3_f32 v5, v18, s81, v20
	s_waitcnt lgkmcnt(2)
	v_max3_f32 v5, v5, v22, v24
	s_waitcnt lgkmcnt(1)
	v_max3_f32 v5, v5, v26, v28
	s_waitcnt lgkmcnt(0)
	v_max3_f32 v3, v5, v30, v32
	ds_read_b64 v[34:35], v9
	v_sub_f32_e32 v9, v20, v3
	v_exp_f32_e32 v20, v9
	v_add_u32_e32 v9, s96, v231
	ds_read_b64 v[36:37], v9
	v_sub_f32_e32 v9, v22, v3
	v_exp_f32_e32 v22, v9
	v_add_u32_e32 v9, s97, v231
	v_sub_f32_e32 v5, v18, v3
	ds_read_b64 v[38:39], v9
	v_sub_f32_e32 v9, v24, v3
	v_exp_f32_e32 v18, v5
	v_exp_f32_e32 v24, v9
	v_add_u32_e32 v9, s34, v231
	ds_read_b64 v[40:41], v9
	v_sub_f32_e32 v9, v26, v3
	v_exp_f32_e32 v26, v9
	v_add_u32_e32 v9, s35, v231
	ds_read_b64 v[42:43], v9
	v_sub_f32_e32 v9, v28, v3
	v_fma_f32 v5, v18, v19, 0
	v_exp_f32_e32 v28, v9
	v_add_u32_e32 v9, s30, v231
	s_waitcnt lgkmcnt(4)
	v_pk_fma_f32 v[18:19], v[18:19], v[34:35], 0 op_sel_hi:[0,1,0]
	v_fmac_f32_e32 v5, v20, v21
	ds_read_b64 v[44:45], v9
	s_waitcnt lgkmcnt(4)
	v_pk_fma_f32 v[18:19], v[20:21], v[36:37], v[18:19] op_sel_hi:[0,1,1]
	v_sub_f32_e32 v9, v30, v3
	v_fmac_f32_e32 v5, v22, v23
	s_waitcnt lgkmcnt(3)
	v_pk_fma_f32 v[18:19], v[22:23], v[38:39], v[18:19] op_sel_hi:[0,1,1]
	v_exp_f32_e32 v20, v9
	v_sub_f32_e32 v3, v32, v3
	v_fmac_f32_e32 v5, v24, v25
	s_waitcnt lgkmcnt(2)
	v_pk_fma_f32 v[18:19], v[24:25], v[40:41], v[18:19] op_sel_hi:[0,1,1]
	v_exp_f32_e32 v24, v3
	v_fmac_f32_e32 v5, v26, v27
	v_fmac_f32_e32 v5, v28, v29
	v_fmac_f32_e32 v5, v20, v31
	v_add_u32_e32 v9, s31, v231
	v_fmac_f32_e32 v5, v24, v33
	v_add_u32_e32 v3, s68, v231
	s_waitcnt lgkmcnt(1)
	v_pk_fma_f32 v[18:19], v[26:27], v[42:43], v[18:19] op_sel_hi:[0,1,1]
	ds_read_b64 v[22:23], v9
	ds_read_b64 v[26:27], v3
	v_div_scale_f32 v3, s[2:3], v5, v5, 1.0
	v_rcp_f32_e32 v9, v3
	v_mbcnt_lo_u32_b32 v30, -1, 0
	v_mbcnt_hi_u32_b32 v30, -1, v30
	s_waitcnt lgkmcnt(2)
	v_pk_fma_f32 v[18:19], v[28:29], v[44:45], v[18:19] op_sel_hi:[0,1,1]
	v_ashrrev_i32_e32 v31, 31, v30
	v_fma_f32 v13, -v3, v9, 1.0
	v_fmac_f32_e32 v9, v13, v9
	v_div_scale_f32 v13, vcc, 1.0, v5, 1.0
	v_mul_f32_e32 v17, v13, v9
	v_fma_f32 v21, -v3, v17, v13
	v_fmac_f32_e32 v17, v21, v9
	v_fma_f32 v3, -v3, v17, v13
	v_div_fmas_f32 v3, v3, v9, v17
	v_lshl_add_u64 v[30:31], v[30:31], 2, s[52:53]
	v_div_fixup_f32 v28, v3, v5, 1.0
	s_cmp_eq_u32 s99, 0x5a5a5a5a
	s_cbranch_scc1 .Llam_cached
	global_load_dword v3, v[30:31], off
	v_mbcnt_lo_u32_b32 v30, -1, 0
	v_mbcnt_hi_u32_b32 v30, -1, v30
	s_mov_b32 s2, 0x3fb8aa3b
	v_ashrrev_i32_e32 v31, 31, v30
	v_lshl_add_u64 v[30:31], v[30:31], 2, s[54:55]
	global_load_dword v5, v[30:31], off
	v_mbcnt_lo_u32_b32 v30, -1, 0
	v_mbcnt_hi_u32_b32 v30, -1, v30
	s_mov_b32 s3, 0xc2ce8ed0
	v_ashrrev_i32_e32 v31, 31, v30
	v_lshl_add_u64 v[30:31], v[30:31], 2, s[56:57]
	s_waitcnt vmcnt(0)
	v_mul_f32_e32 v9, v3, v5
	s_nop 1
	v_mov_b32_dpp v9, v9 quad_perm:[1,0,3,2] row_mask:0xf bank_mask:0xf bound_ctrl:1
	v_fmac_f32_e32 v9, v3, v5
	s_nop 1
	v_add_f32_dpp v3, v9, v9 quad_perm:[2,3,0,1] row_mask:0xf bank_mask:0xf bound_ctrl:1
	s_nop 1
	v_add_f32_dpp v3, v3, v3 row_half_mirror row_mask:0xf bank_mask:0xf bound_ctrl:1
	s_nop 1
	v_add_f32_dpp v3, v3, v3 row_mirror row_mask:0xf bank_mask:0xf bound_ctrl:1
	v_mov_b32_e32 v5, v3
	s_nop 1
	v_permlane16_swap_b32_e32 v3, v5
	v_add_f32_e32 v3, v3, v5
	v_mov_b32_e32 v5, v3
	s_nop 1
	v_permlane32_swap_b32_e32 v3, v5
	v_add_f32_e32 v3, v3, v5
	global_load_dword v5, v[30:31], off
	v_mbcnt_lo_u32_b32 v30, -1, 0
	v_mbcnt_hi_u32_b32 v30, -1, v30
	v_cmp_ngt_f32_e32 vcc, s3, v3
	v_ashrrev_i32_e32 v31, 31, v30
	v_lshl_add_u64 v[30:31], v[30:31], 2, s[58:59]
	global_load_dword v9, v[30:31], off
	s_waitcnt vmcnt(0)
	v_mul_f32_e32 v13, v5, v9
	s_nop 1
	v_mov_b32_dpp v13, v13 quad_perm:[1,0,3,2] row_mask:0xf bank_mask:0xf bound_ctrl:1
	v_fmac_f32_e32 v13, v5, v9
	s_nop 1
	v_add_f32_dpp v5, v13, v13 quad_perm:[2,3,0,1] row_mask:0xf bank_mask:0xf bound_ctrl:1
	s_nop 1
	v_add_f32_dpp v5, v5, v5 row_half_mirror row_mask:0xf bank_mask:0xf bound_ctrl:1
	s_nop 1
	v_add_f32_dpp v5, v5, v5 row_mirror row_mask:0xf bank_mask:0xf bound_ctrl:1
	v_mov_b32_e32 v9, v5
	s_nop 1
	v_permlane16_swap_b32_e32 v5, v9
	v_add_f32_e32 v5, v5, v9
	v_mov_b32_e32 v9, v5
	s_nop 1
	v_permlane32_swap_b32_e32 v5, v9
	v_add_f32_e32 v5, v5, v9
	v_mul_f32_e32 v9, 0x3fb8aa3b, v3
	v_fma_f32 v13, v3, s2, -v9
	v_rndne_f32_e32 v17, v9
	v_fmac_f32_e32 v13, 0x32a5705f, v3
	v_sub_f32_e32 v9, v9, v17
	v_add_f32_e32 v9, v9, v13
	v_exp_f32_e32 v9, v9
	v_cvt_i32_f32_e32 v13, v17
	v_ldexp_f32 v9, v9, v13
	v_cndmask_b32_e32 v9, 0, v9, vcc
	v_cmp_nlt_f32_e32 vcc, s16, v3
	s_nop 1
	v_cndmask_b32_e32 v3, v228, v9, vcc
	v_mul_f32_e32 v9, 0x3fb8aa3b, v5
	v_fma_f32 v13, v5, s2, -v9
	v_rndne_f32_e32 v17, v9
	v_fmac_f32_e32 v13, 0x32a5705f, v5
	v_sub_f32_e32 v9, v9, v17
	v_add_f32_e32 v9, v9, v13
	v_exp_f32_e32 v9, v9
	v_cvt_i32_f32_e32 v13, v17
	v_cmp_ngt_f32_e32 vcc, s3, v5
	v_ldexp_f32 v9, v9, v13
	s_nop 0
	v_cndmask_b32_e32 v9, 0, v9, vcc
	v_cmp_nlt_f32_e32 vcc, s16, v5
	s_nop 1
	v_cndmask_b32_e32 v5, v228, v9, vcc
	v_sub_f32_e32 v3, v3, v5
	s_nop 0
	v_readfirstlane_b32 s2, v3
	s_nop 1
	s_mov_b32 s98, s2
	s_mov_b32 s99, 0x5a5a5a5a
	s_branch .Llam_done
.Llam_cached:
	s_mov_b32 s2, s98
.Llam_done:
	v_or_b32_e32 v3, s62, v232
	v_lshlrev_b32_e32 v3, 1, v3
	v_add_f32_e32 v32, s2, v229
	s_add_i32 s2, s25, s70
	s_ashr_i32 s3, s2, 31
	s_lshl_b64 s[16:17], s[2:3], 10
	s_add_u32 s16, s72, s16
	s_addc_u32 s17, s73, s17
	global_load_dword v5, v3, s[16:17]
	s_mov_b32 s16, 0xf800000
	s_lshl_b64 s[2:3], s[2:3], 11
	s_add_u32 s2, s76, s2
	s_addc_u32 s3, s77, s3
	s_waitcnt vmcnt(0)
	v_lshlrev_b32_e32 v30, 16, v5
	v_and_b32_e32 v31, 0xffff0000, v5
	v_pk_fma_f32 v[0:1], v[4:5], v[6:7], v[0:1] op_sel_hi:[0,1,1]
	s_waitcnt lgkmcnt(1)
	v_pk_fma_f32 v[4:5], v[20:21], v[22:23], v[18:19] op_sel_hi:[0,1,1]
	s_waitcnt lgkmcnt(0)
	v_pk_fma_f32 v[4:5], v[24:25], v[26:27], v[4:5] op_sel_hi:[0,1,1]
	v_pk_fma_f32 v[0:1], v[8:9], v[10:11], v[0:1] op_sel_hi:[0,1,1]
	v_pk_mul_f32 v[4:5], v[28:29], v[4:5] op_sel_hi:[0,1]
	v_pk_fma_f32 v[0:1], v[12:13], v[14:15], v[0:1] op_sel_hi:[0,1,1]
	v_pk_mul_f32 v[4:5], v[4:5], v[32:33] op_sel_hi:[1,0]
	s_nop 0
	v_pk_fma_f32 v[0:1], v[16:17], v[0:1], v[4:5] op_sel_hi:[0,1,1] neg_lo:[0,0,1] neg_hi:[0,0,1]
	v_pk_mul_f32 v[4:5], v[0:1], v[0:1]
	s_nop 0
	v_add_f32_e32 v4, v4, v5
	s_nop 1
	v_add_f32_dpp v4, v4, v4 quad_perm:[1,0,3,2] row_mask:0xf bank_mask:0xf bound_ctrl:1
	s_nop 1
	v_add_f32_dpp v4, v4, v4 quad_perm:[2,3,0,1] row_mask:0xf bank_mask:0xf bound_ctrl:1
	s_nop 1
	v_add_f32_dpp v4, v4, v4 row_half_mirror row_mask:0xf bank_mask:0xf bound_ctrl:1
	s_nop 1
	v_add_f32_dpp v4, v4, v4 row_mirror row_mask:0xf bank_mask:0xf bound_ctrl:1
	v_mov_b32_e32 v5, v4
	s_nop 1
	v_permlane16_swap_b32_e32 v4, v5
	v_add_f32_e32 v4, v4, v5
	v_mov_b32_e32 v5, v4
	s_nop 1
	v_permlane32_swap_b32_e32 v4, v5
	v_add_f32_e32 v4, v4, v5
	v_fmamk_f32 v4, v4, 0x3c000000, v224
	v_cmp_gt_f32_e32 vcc, s16, v4
	v_mul_f32_e32 v5, 0x4f800000, v4
	s_nop 0
	v_cndmask_b32_e32 v4, v4, v5, vcc
	v_sqrt_f32_e32 v5, v4
	s_nop 0
	v_add_u32_e32 v6, -1, v5
	v_fma_f32 v7, -v6, v5, v4
	v_cmp_ge_f32_e64 s[16:17], 0, v7
	v_add_u32_e32 v7, 1, v5
	s_nop 0
	v_cndmask_b32_e64 v6, v5, v6, s[16:17]
	v_fma_f32 v5, -v7, v5, v4
	v_cmp_lt_f32_e64 s[16:17], 0, v5
	s_nop 1
	v_cndmask_b32_e64 v5, v6, v7, s[16:17]
	v_mul_f32_e32 v6, 0x37800000, v5
	v_cndmask_b32_e32 v5, v5, v6, vcc
	v_cmp_class_f32_e32 vcc, v4, v225
	s_nop 1
	v_cndmask_b32_e32 v4, v5, v4, vcc
	v_div_scale_f32 v5, s[16:17], v4, v4, 1.0
	v_rcp_f32_e32 v6, v5
	s_movk_i32 s16, 0x7fff
	v_fma_f32 v7, -v5, v6, 1.0
	v_fmac_f32_e32 v6, v7, v6
	v_div_scale_f32 v7, vcc, 1.0, v4, 1.0
	v_mul_f32_e32 v8, v7, v6
	v_fma_f32 v9, -v5, v8, v7
	v_fmac_f32_e32 v8, v9, v6
	v_fma_f32 v5, -v5, v8, v7
	v_div_fmas_f32 v5, v5, v6, v8
	v_div_fixup_f32 v4, v5, v4, 1.0
	v_pk_mul_f32 v[0:1], v[0:1], v[4:5] op_sel_hi:[1,0]
	global_load_dwordx2 v[4:5], v[210:211], off
	s_waitcnt vmcnt(0)
	v_pk_mul_f32 v[0:1], v[4:5], v[0:1]
	s_nop 0
	v_pk_mul_f32 v[0:1], v[0:1], v[30:31]
	s_nop 0
	v_and_b32_sdwa v5, v0, v226 dst_sel:DWORD dst_unused:UNUSED_PAD src0_sel:WORD_1 src1_sel:DWORD
	v_and_b32_sdwa v4, v1, v226 dst_sel:DWORD dst_unused:UNUSED_PAD src0_sel:WORD_1 src1_sel:DWORD
	v_add3_u32 v0, v0, v5, s16
	v_add3_u32 v1, v1, v4, s16
	v_lshrrev_b32_e32 v0, 16, v0
	s_mov_b32 s16, 0xffff0000
	v_and_or_b32 v0, v1, s16, v0
	global_store_dword v3, v0, s[2:3]
	v_readlane_b32 s2, v247, 10
	s_add_i32 s69, s69, s2
	s_cmpk_lt_i32 s69, 0x200
	s_barrier
	s_cbranch_scc0 .LBB0_405

	.amdhsa_kernel _Z9hymba_fwd4Args
		.amdhsa_group_segment_fixed_size 0
		.amdhsa_private_segment_fixed_size 0
		.amdhsa_kernarg_size 440
		.amdhsa_user_sgpr_count 2
		.amdhsa_user_sgpr_dispatch_ptr 0
		.amdhsa_user_sgpr_queue_ptr 0
		.amdhsa_user_sgpr_kernarg_segment_ptr 1
		.amdhsa_user_sgpr_dispatch_id 0
		.amdhsa_user_sgpr_kernarg_preload_length 0
		.amdhsa_user_sgpr_kernarg_preload_offset 0
		.amdhsa_user_sgpr_private_segment_size 0
		.amdhsa_uses_dynamic_stack 0
		.amdhsa_enable_private_segment 0
		.amdhsa_system_sgpr_workgroup_id_x 1
		.amdhsa_system_sgpr_workgroup_id_y 0
		.amdhsa_system_sgpr_workgroup_id_z 0
		.amdhsa_system_sgpr_workgroup_info 0
		.amdhsa_system_vgpr_workitem_id 0
		.amdhsa_next_free_vgpr 248
		.amdhsa_next_free_sgpr 102
		.amdhsa_accum_offset 248
		.amdhsa_reserve_vcc 1
		.amdhsa_float_round_mode_32 0
		.amdhsa_float_round_mode_16_64 0
		.amdhsa_float_denorm_mode_32 3
		.amdhsa_float_denorm_mode_16_64 3
		.amdhsa_dx10_clamp 1
		.amdhsa_ieee_mode 1
		.amdhsa_fp16_overflow 0
		.amdhsa_tg_split 0
		.amdhsa_exception_fp_ieee_invalid_op 0
		.amdhsa_exception_fp_denorm_src 0
		.amdhsa_exception_fp_ieee_div_zero 0
		.amdhsa_exception_fp_ieee_overflow 0
		.amdhsa_exception_fp_ieee_underflow 0
		.amdhsa_exception_fp_ieee_inexact 0
		.amdhsa_exception_int_div_zero 0
	.end_amdhsa_kernel

amdhsa.kernels:
  - .agpr_count:     0
    .args:
      - .offset:         0
        .size:           184
        .value_kind:     by_value
      - .offset:         184
        .size:           4
        .value_kind:     hidden_block_count_x
      - .offset:         188
        .size:           4
        .value_kind:     hidden_block_count_y
      - .offset:         192
        .size:           4
        .value_kind:     hidden_block_count_z
      - .offset:         196
        .size:           2
        .value_kind:     hidden_group_size_x
      - .offset:         198
        .size:           2
        .value_kind:     hidden_group_size_y
      - .offset:         200
        .size:           2
        .value_kind:     hidden_group_size_z
      - .offset:         202
        .size:           2
        .value_kind:     hidden_remainder_x
      - .offset:         204
        .size:           2
        .value_kind:     hidden_remainder_y
      - .offset:         206
        .size:           2
        .value_kind:     hidden_remainder_z
      - .offset:         224
        .size:           8
        .value_kind:     hidden_global_offset_x
      - .offset:         232
        .size:           8
        .value_kind:     hidden_global_offset_y
      - .offset:         240
        .size:           8
        .value_kind:     hidden_global_offset_z
      - .offset:         248
        .size:           2
        .value_kind:     hidden_grid_dims
      - .offset:         304
        .size:           4
        .value_kind:     hidden_dynamic_lds_size
    .group_segment_fixed_size: 0
    .kernarg_segment_align: 8
    .kernarg_segment_size: 440
    .language:       OpenCL C
    .language_version:
      - 2
      - 0
    .max_flat_workgroup_size: 512
    .name:           _Z9hymba_fwd4Args
    .private_segment_fixed_size: 0
    .sgpr_count:     108
    .sgpr_spill_count: 65
    .symbol:         _Z9hymba_fwd4Args.kd
    .uniform_work_group_size: 1
    .uses_dynamic_stack: false
    .vgpr_count:     248
    .vgpr_spill_count: 0
    .wavefront_size: 64
